# local seams: no release hop (every workgroup polls the 32 arrival flags of its XCD), first poll issued before the L1 invalidate
# baseline (speedup 1.0000x reference)
; __device__ __forceinline__ unsigned xb_ld(unsigned* p)              { return __hip_atomic_load(p, __ATOMIC_RELAXED, __HIP_MEMORY_SCOPE_AGENT); }
; __device__ __forceinline__ unsigned xb_add(unsigned* p, unsigned v) { return __hip_atomic_fetch_add(p, v, __ATOMIC_RELAXED, __HIP_MEMORY_SCOPE_AGENT); }
; #define XB_SPIN(cond, bar) do { unsigned _sp = 0; while (cond) { __builtin_amdgcn_s_sleep(1); \
;     if ((++_sp & 255u) == 0u) { if (xb_ld(&(bar)[XB_TMO])) break; if (_sp > XB_SPIN_CAP) { atomicAdd(&(bar)[XB_TMO], 1u); break; } } } } while (0)
; __device__ __forceinline__ void xcd_barrier(const XcdBarrier& b) {
;     asm volatile("s_waitcnt vmcnt(0)" ::: "memory");
;     __syncthreads();
;     if (threadIdx.x == 0) {
;         unsigned* bar = b.bar;
;         __builtin_amdgcn_s_waitcnt(0);
;         unsigned nloc = b.st[0], nx = b.st[1];
;         if (nloc == 0u) { xcd_barrier_complete(bar, b.x, nloc, nx); b.st[0] = nloc; b.st[1] = nx; }
;         const unsigned old = xb_add(&bar[XB_XSUB(b.x)], 1u);
;         const unsigned gen = old / nloc;
;         if (old + 1u == (gen + 1u) * nloc) {
;             __builtin_amdgcn_fence(__ATOMIC_RELEASE, "agent");
;             asm volatile("s_waitcnt vmcnt(0)" ::: "memory");
;             const unsigned og = xb_add(&bar[XB_TOP], 1u);
;             const unsigned tg = og / nx;
;             if (og + 1u == (tg + 1u) * nx) xb_add(&bar[XB_TOPGEN], 1u);
;             else XB_SPIN(xb_ld(&bar[XB_TOPGEN]) == tg, bar);
;             __builtin_amdgcn_fence(__ATOMIC_ACQUIRE, "agent");
;             xb_add(&bar[XB_XGEN(b.x)], 1u);
;             asm volatile("s_waitcnt vmcnt(0)" ::: "memory");
;         } else {
;             XB_SPIN(xb_ld(&bar[XB_XGEN(b.x)]) == gen, bar);
;             __builtin_amdgcn_fence(__ATOMIC_ACQUIRE, "agent");
;             asm volatile("s_waitcnt vmcnt(0)" ::: "memory");
;         }
;     }
;     __syncthreads();
; }
.LBB0_344:
	s_cmp_lt_i32 s92, 3
	s_cselect_b64 s[8:9], -1, 0
	s_cmp_gt_i32 s93, 2
	s_cselect_b64 s[0:1], -1, 0
	s_and_b64 s[0:1], s[8:9], s[0:1]
	s_andn2_b64 vcc, exec, s[0:1]
	s_cbranch_vccnz .LBB0_441
	s_andn2_b64 vcc, exec, s[10:11]
	s_cbranch_vccnz .LBB0_395
	s_waitcnt vmcnt(0)
	v_cmp_eq_u32_e32 vcc, 0, v254
	s_waitcnt vmcnt(0) lgkmcnt(0)
	s_barrier
	s_and_saveexec_b64 s[0:1], vcc
	s_cbranch_execz .LBB0_394
	s_cmp_eq_u32 s98, 1
	s_cbranch_scc0 .Lxfull_2
	s_add_i32 s99, s99, 1
	s_and_b32 s4, s2, 7
	s_lshl_b32 s4, s4, 8
	s_add_u32 s4, s90, s4
	s_addc_u32 s5, s91, 0
	s_lshr_b32 s3, s2, 3
	v_mov_b32_e32 v0, s99
	v_mov_b32_e32 v1, s3
	v_lshlrev_b32_e32 v1, 2, v1
	global_store_dword v1, v0, s[4:5] offset:512
	s_mov_b64 s[6:7], exec
	s_mov_b32 exec_lo, -1
	s_mov_b32 exec_hi, 0
	v_lshlrev_b32_e32 v2, 2, v251
	global_load_dword v3, v2, s[4:5] offset:512 sc1
	buffer_inv sc1
	s_mov_b32 s3, 0
	s_waitcnt vmcnt(1)
.Lxpoll_2:
	v_cmp_le_u32_e32 vcc, s99, v3
	s_nop 3
	s_cmp_eq_u32 vcc_lo, -1
	s_cbranch_scc1 .Lxdone_2
	s_sleep 1
	s_add_i32 s3, s3, 1
	s_cmp_lt_u32 s3, 0x100000
	s_cbranch_scc0 .Lxdone_2
	global_load_dword v3, v2, s[4:5] offset:512 sc1
	s_waitcnt vmcnt(0)
	s_branch .Lxpoll_2
.Lxdone_2:
	s_mov_b64 exec, s[6:7]
	s_waitcnt vmcnt(0)
	s_branch .LBB0_394

; __device__ __forceinline__ unsigned xb_ld(unsigned* p)              { return __hip_atomic_load(p, __ATOMIC_RELAXED, __HIP_MEMORY_SCOPE_AGENT); }
; __device__ __forceinline__ unsigned xb_add(unsigned* p, unsigned v) { return __hip_atomic_fetch_add(p, v, __ATOMIC_RELAXED, __HIP_MEMORY_SCOPE_AGENT); }
; #define XB_SPIN(cond, bar) do { unsigned _sp = 0; while (cond) { __builtin_amdgcn_s_sleep(1); \
;     if ((++_sp & 255u) == 0u) { if (xb_ld(&(bar)[XB_TMO])) break; if (_sp > XB_SPIN_CAP) { atomicAdd(&(bar)[XB_TMO], 1u); break; } } } } while (0)
; __device__ __forceinline__ void xcd_barrier(const XcdBarrier& b) {
;     asm volatile("s_waitcnt vmcnt(0)" ::: "memory");
;     __syncthreads();
;     if (threadIdx.x == 0) {
;         unsigned* bar = b.bar;
;         __builtin_amdgcn_s_waitcnt(0);
;         unsigned nloc = b.st[0], nx = b.st[1];
;         if (nloc == 0u) { xcd_barrier_complete(bar, b.x, nloc, nx); b.st[0] = nloc; b.st[1] = nx; }
;         const unsigned old = xb_add(&bar[XB_XSUB(b.x)], 1u);
;         const unsigned gen = old / nloc;
;         if (old + 1u == (gen + 1u) * nloc) {
;             __builtin_amdgcn_fence(__ATOMIC_RELEASE, "agent");
;             asm volatile("s_waitcnt vmcnt(0)" ::: "memory");
;             const unsigned og = xb_add(&bar[XB_TOP], 1u);
;             const unsigned tg = og / nx;
;             if (og + 1u == (tg + 1u) * nx) xb_add(&bar[XB_TOPGEN], 1u);
;             else XB_SPIN(xb_ld(&bar[XB_TOPGEN]) == tg, bar);
;             __builtin_amdgcn_fence(__ATOMIC_ACQUIRE, "agent");
;             xb_add(&bar[XB_XGEN(b.x)], 1u);
;             asm volatile("s_waitcnt vmcnt(0)" ::: "memory");
;         } else {
;             XB_SPIN(xb_ld(&bar[XB_XGEN(b.x)]) == gen, bar);
;             __builtin_amdgcn_fence(__ATOMIC_ACQUIRE, "agent");
;             asm volatile("s_waitcnt vmcnt(0)" ::: "memory");
;         }
;     }
;     __syncthreads();
; }
.LBB0_441:
	s_cmp_lt_i32 s92, 4
	s_cselect_b64 s[10:11], -1, 0
	s_cmp_gt_i32 s93, 3
	s_cselect_b64 s[0:1], -1, 0
	s_and_b64 s[0:1], s[10:11], s[0:1]
	s_andn2_b64 vcc, exec, s[0:1]
	s_cbranch_vccnz .LBB0_622
	s_andn2_b64 vcc, exec, s[8:9]
	s_cbranch_vccnz .LBB0_492
	s_waitcnt vmcnt(0)
	v_cmp_eq_u32_e32 vcc, 0, v254
	s_waitcnt vmcnt(0) lgkmcnt(0)
	s_barrier
	s_and_saveexec_b64 s[0:1], vcc
	s_cbranch_execz .LBB0_491
	s_cmp_eq_u32 s98, 1
	s_cbranch_scc0 .Lxfull_3
	s_add_i32 s99, s99, 1
	s_and_b32 s4, s2, 7
	s_lshl_b32 s4, s4, 8
	s_add_u32 s4, s90, s4
	s_addc_u32 s5, s91, 0
	s_lshr_b32 s3, s2, 3
	v_mov_b32_e32 v0, s99
	v_mov_b32_e32 v1, s3
	v_lshlrev_b32_e32 v1, 2, v1
	global_store_dword v1, v0, s[4:5] offset:512
	s_mov_b64 s[6:7], exec
	s_mov_b32 exec_lo, -1
	s_mov_b32 exec_hi, 0
	v_lshlrev_b32_e32 v2, 2, v251
	global_load_dword v3, v2, s[4:5] offset:512 sc1
	buffer_inv sc1
	s_mov_b32 s3, 0
	s_waitcnt vmcnt(1)

; __device__ __forceinline__ unsigned xb_ld(unsigned* p)              { return __hip_atomic_load(p, __ATOMIC_RELAXED, __HIP_MEMORY_SCOPE_AGENT); }
; __device__ __forceinline__ unsigned xb_add(unsigned* p, unsigned v) { return __hip_atomic_fetch_add(p, v, __ATOMIC_RELAXED, __HIP_MEMORY_SCOPE_AGENT); }
; #define XB_SPIN(cond, bar) do { unsigned _sp = 0; while (cond) { __builtin_amdgcn_s_sleep(1); \
;     if ((++_sp & 255u) == 0u) { if (xb_ld(&(bar)[XB_TMO])) break; if (_sp > XB_SPIN_CAP) { atomicAdd(&(bar)[XB_TMO], 1u); break; } } } } while (0)
; __device__ __forceinline__ void xcd_barrier(const XcdBarrier& b) {
;     asm volatile("s_waitcnt vmcnt(0)" ::: "memory");
;     __syncthreads();
;     if (threadIdx.x == 0) {
;         unsigned* bar = b.bar;
;         __builtin_amdgcn_s_waitcnt(0);
;         unsigned nloc = b.st[0], nx = b.st[1];
;         if (nloc == 0u) { xcd_barrier_complete(bar, b.x, nloc, nx); b.st[0] = nloc; b.st[1] = nx; }
;         const unsigned old = xb_add(&bar[XB_XSUB(b.x)], 1u);
;         const unsigned gen = old / nloc;
;         if (old + 1u == (gen + 1u) * nloc) {
;             __builtin_amdgcn_fence(__ATOMIC_RELEASE, "agent");
;             asm volatile("s_waitcnt vmcnt(0)" ::: "memory");
;             const unsigned og = xb_add(&bar[XB_TOP], 1u);
;             const unsigned tg = og / nx;
;             if (og + 1u == (tg + 1u) * nx) xb_add(&bar[XB_TOPGEN], 1u);
;             else XB_SPIN(xb_ld(&bar[XB_TOPGEN]) == tg, bar);
;             __builtin_amdgcn_fence(__ATOMIC_ACQUIRE, "agent");
;             xb_add(&bar[XB_XGEN(b.x)], 1u);
;             asm volatile("s_waitcnt vmcnt(0)" ::: "memory");
;         } else {
;             XB_SPIN(xb_ld(&bar[XB_XGEN(b.x)]) == gen, bar);
;             __builtin_amdgcn_fence(__ATOMIC_ACQUIRE, "agent");
;             asm volatile("s_waitcnt vmcnt(0)" ::: "memory");
;         }
;     }
;     __syncthreads();
; }
.LBB0_704:
	s_cmp_lt_i32 s92, 6
	s_cselect_b64 s[0:1], -1, 0
	s_cmp_gt_i32 s93, 5
	s_cselect_b64 s[4:5], -1, 0
	s_and_b64 s[4:5], s[0:1], s[4:5]
	v_readlane_b32 s64, v255, 4
	s_andn2_b64 vcc, exec, s[4:5]
	v_readlane_b32 s68, v255, 8
	v_readlane_b32 s69, v255, 9
	v_readlane_b32 s65, v255, 5
	v_readlane_b32 s66, v255, 6
	v_readlane_b32 s67, v255, 7
	v_readlane_b32 s70, v255, 10
	v_readlane_b32 s71, v255, 11
	v_readlane_b32 s72, v255, 12
	v_readlane_b32 s73, v255, 13
	v_readlane_b32 s74, v255, 14
	v_readlane_b32 s75, v255, 15
	v_readlane_b32 s76, v255, 16
	v_readlane_b32 s77, v255, 17
	v_readlane_b32 s78, v255, 18
	v_readlane_b32 s79, v255, 19
	s_cbranch_vccnz .LBB0_765
	s_andn2_b64 vcc, exec, s[80:81]
	s_cbranch_vccnz .LBB0_755
	s_waitcnt vmcnt(0)
	v_cmp_eq_u32_e32 vcc, 0, v254
	s_waitcnt vmcnt(0) lgkmcnt(0)
	s_barrier
	s_and_saveexec_b64 s[4:5], vcc
	s_cbranch_execz .LBB0_754
	s_cmp_eq_u32 s98, 1
	s_cbranch_scc0 .Lxfull_5
	s_add_i32 s99, s99, 1
	s_and_b32 s6, s2, 7
	s_lshl_b32 s6, s6, 8
	s_add_u32 s6, s90, s6
	s_addc_u32 s7, s91, 0
	s_lshr_b32 s3, s2, 3
	v_mov_b32_e32 v0, s99
	v_mov_b32_e32 v1, s3
	v_lshlrev_b32_e32 v1, 2, v1
	global_store_dword v1, v0, s[6:7] offset:512
	s_mov_b64 s[8:9], exec
	s_mov_b32 exec_lo, -1
	s_mov_b32 exec_hi, 0
	v_lshlrev_b32_e32 v2, 2, v251
	global_load_dword v3, v2, s[6:7] offset:512 sc1
	buffer_inv sc1
	s_mov_b32 s3, 0
	s_waitcnt vmcnt(1)
.Lxpoll_5:
	v_cmp_le_u32_e32 vcc, s99, v3
	s_nop 3
	s_cmp_eq_u32 vcc_lo, -1
	s_cbranch_scc1 .Lxdone_5
	s_sleep 1
	s_add_i32 s3, s3, 1
	s_cmp_lt_u32 s3, 0x100000
	s_cbranch_scc0 .Lxdone_5
	global_load_dword v3, v2, s[6:7] offset:512 sc1
	s_waitcnt vmcnt(0)
	s_branch .Lxpoll_5
.Lxdone_5:
	s_mov_b64 exec, s[8:9]
	s_waitcnt vmcnt(0)
	s_branch .LBB0_754

; __device__ __forceinline__ unsigned xb_ld(unsigned* p)              { return __hip_atomic_load(p, __ATOMIC_RELAXED, __HIP_MEMORY_SCOPE_AGENT); }
; __device__ __forceinline__ unsigned xb_add(unsigned* p, unsigned v) { return __hip_atomic_fetch_add(p, v, __ATOMIC_RELAXED, __HIP_MEMORY_SCOPE_AGENT); }
; #define XB_SPIN(cond, bar) do { unsigned _sp = 0; while (cond) { __builtin_amdgcn_s_sleep(1); \
;     if ((++_sp & 255u) == 0u) { if (xb_ld(&(bar)[XB_TMO])) break; if (_sp > XB_SPIN_CAP) { atomicAdd(&(bar)[XB_TMO], 1u); break; } } } } while (0)
; __device__ __forceinline__ void xcd_barrier(const XcdBarrier& b) {
;     asm volatile("s_waitcnt vmcnt(0)" ::: "memory");
;     __syncthreads();
;     if (threadIdx.x == 0) {
;         unsigned* bar = b.bar;
;         __builtin_amdgcn_s_waitcnt(0);
;         unsigned nloc = b.st[0], nx = b.st[1];
;         if (nloc == 0u) { xcd_barrier_complete(bar, b.x, nloc, nx); b.st[0] = nloc; b.st[1] = nx; }
;         const unsigned old = xb_add(&bar[XB_XSUB(b.x)], 1u);
;         const unsigned gen = old / nloc;
;         if (old + 1u == (gen + 1u) * nloc) {
;             __builtin_amdgcn_fence(__ATOMIC_RELEASE, "agent");
;             asm volatile("s_waitcnt vmcnt(0)" ::: "memory");
;             const unsigned og = xb_add(&bar[XB_TOP], 1u);
;             const unsigned tg = og / nx;
;             if (og + 1u == (tg + 1u) * nx) xb_add(&bar[XB_TOPGEN], 1u);
;             else XB_SPIN(xb_ld(&bar[XB_TOPGEN]) == tg, bar);
;             __builtin_amdgcn_fence(__ATOMIC_ACQUIRE, "agent");
;             xb_add(&bar[XB_XGEN(b.x)], 1u);
;             asm volatile("s_waitcnt vmcnt(0)" ::: "memory");
;         } else {
;             XB_SPIN(xb_ld(&bar[XB_XGEN(b.x)]) == gen, bar);
;             __builtin_amdgcn_fence(__ATOMIC_ACQUIRE, "agent");
;             asm volatile("s_waitcnt vmcnt(0)" ::: "memory");
;         }
;     }
;     __syncthreads();
; }
.LBB0_765:
	s_cmp_lt_i32 s92, 7
	s_cselect_b64 s[40:41], -1, 0
	s_cmp_gt_i32 s93, 6
	s_cselect_b64 s[4:5], -1, 0
	s_and_b64 s[4:5], s[40:41], s[4:5]
	s_andn2_b64 vcc, exec, s[4:5]
	s_cbranch_vccnz .LBB0_890
	s_andn2_b64 vcc, exec, s[0:1]
	s_cbranch_vccnz .LBB0_816
	s_waitcnt vmcnt(0)
	v_cmp_eq_u32_e32 vcc, 0, v254
	s_waitcnt vmcnt(0) lgkmcnt(0)
	s_barrier
	s_and_saveexec_b64 s[0:1], vcc
	s_cbranch_execz .LBB0_815
	s_cmp_eq_u32 s98, 1
	s_cbranch_scc0 .Lxfull_6
	s_add_i32 s99, s99, 1
	s_and_b32 s4, s2, 7
	s_lshl_b32 s4, s4, 8
	s_add_u32 s4, s90, s4
	s_addc_u32 s5, s91, 0
	s_lshr_b32 s3, s2, 3
	v_mov_b32_e32 v0, s99
	v_mov_b32_e32 v1, s3
	v_lshlrev_b32_e32 v1, 2, v1
	global_store_dword v1, v0, s[4:5] offset:512
	s_mov_b64 s[6:7], exec
	s_mov_b32 exec_lo, -1
	s_mov_b32 exec_hi, 0
	v_lshlrev_b32_e32 v2, 2, v251
	global_load_dword v3, v2, s[4:5] offset:512 sc1
	buffer_inv sc1
	s_mov_b32 s3, 0
	s_waitcnt vmcnt(1)

; __device__ __forceinline__ unsigned xb_ld(unsigned* p)              { return __hip_atomic_load(p, __ATOMIC_RELAXED, __HIP_MEMORY_SCOPE_AGENT); }
; __device__ __forceinline__ unsigned xb_add(unsigned* p, unsigned v) { return __hip_atomic_fetch_add(p, v, __ATOMIC_RELAXED, __HIP_MEMORY_SCOPE_AGENT); }
; #define XB_SPIN(cond, bar) do { unsigned _sp = 0; while (cond) { __builtin_amdgcn_s_sleep(1); \
;     if ((++_sp & 255u) == 0u) { if (xb_ld(&(bar)[XB_TMO])) break; if (_sp > XB_SPIN_CAP) { atomicAdd(&(bar)[XB_TMO], 1u); break; } } } } while (0)
; __device__ __forceinline__ void xcd_barrier(const XcdBarrier& b) {
;     asm volatile("s_waitcnt vmcnt(0)" ::: "memory");
;     __syncthreads();
;     if (threadIdx.x == 0) {
;         unsigned* bar = b.bar;
;         __builtin_amdgcn_s_waitcnt(0);
;         unsigned nloc = b.st[0], nx = b.st[1];
;         if (nloc == 0u) { xcd_barrier_complete(bar, b.x, nloc, nx); b.st[0] = nloc; b.st[1] = nx; }
;         const unsigned old = xb_add(&bar[XB_XSUB(b.x)], 1u);
;         const unsigned gen = old / nloc;
;         if (old + 1u == (gen + 1u) * nloc) {
;             __builtin_amdgcn_fence(__ATOMIC_RELEASE, "agent");
;             asm volatile("s_waitcnt vmcnt(0)" ::: "memory");
;             const unsigned og = xb_add(&bar[XB_TOP], 1u);
;             const unsigned tg = og / nx;
;             if (og + 1u == (tg + 1u) * nx) xb_add(&bar[XB_TOPGEN], 1u);
;             else XB_SPIN(xb_ld(&bar[XB_TOPGEN]) == tg, bar);
;             __builtin_amdgcn_fence(__ATOMIC_ACQUIRE, "agent");
;             xb_add(&bar[XB_XGEN(b.x)], 1u);
;             asm volatile("s_waitcnt vmcnt(0)" ::: "memory");
;         } else {
;             XB_SPIN(xb_ld(&bar[XB_XGEN(b.x)]) == gen, bar);
;             __builtin_amdgcn_fence(__ATOMIC_ACQUIRE, "agent");
;             asm volatile("s_waitcnt vmcnt(0)" ::: "memory");
;         }
;     }
;     __syncthreads();
; }
.LBB0_983:
	s_cmp_lt_i32 s92, 9
	s_cselect_b64 s[10:11], -1, 0
	s_cmp_gt_i32 s93, 8
	s_cselect_b64 s[0:1], -1, 0
	s_and_b64 s[0:1], s[10:11], s[0:1]
	s_andn2_b64 vcc, exec, s[0:1]
	s_cbranch_vccnz .LBB0_1056
	s_andn2_b64 vcc, exec, s[6:7]
	s_cbranch_vccnz .LBB0_1034
	s_waitcnt vmcnt(0)
	v_cmp_eq_u32_e32 vcc, 0, v254
	s_waitcnt vmcnt(0) lgkmcnt(0)
	s_barrier
	s_and_saveexec_b64 s[0:1], vcc
	s_cbranch_execz .LBB0_1033
	s_cmp_eq_u32 s98, 1
	s_cbranch_scc0 .Lxfull_8
	s_add_i32 s99, s99, 1
	s_and_b32 s4, s2, 7
	s_lshl_b32 s4, s4, 8
	s_add_u32 s4, s90, s4
	s_addc_u32 s5, s91, 0
	s_lshr_b32 s3, s2, 3
	v_mov_b32_e32 v0, s99
	v_mov_b32_e32 v1, s3
	v_lshlrev_b32_e32 v1, 2, v1
	global_store_dword v1, v0, s[4:5] offset:512
	s_mov_b64 s[6:7], exec
	s_mov_b32 exec_lo, -1
	s_mov_b32 exec_hi, 0
	v_lshlrev_b32_e32 v2, 2, v251
	global_load_dword v3, v2, s[4:5] offset:512 sc1
	buffer_inv sc1
	s_mov_b32 s3, 0
	s_waitcnt vmcnt(1)

; __device__ __forceinline__ unsigned xb_ld(unsigned* p)              { return __hip_atomic_load(p, __ATOMIC_RELAXED, __HIP_MEMORY_SCOPE_AGENT); }
; __device__ __forceinline__ unsigned xb_add(unsigned* p, unsigned v) { return __hip_atomic_fetch_add(p, v, __ATOMIC_RELAXED, __HIP_MEMORY_SCOPE_AGENT); }
; #define XB_SPIN(cond, bar) do { unsigned _sp = 0; while (cond) { __builtin_amdgcn_s_sleep(1); \
;     if ((++_sp & 255u) == 0u) { if (xb_ld(&(bar)[XB_TMO])) break; if (_sp > XB_SPIN_CAP) { atomicAdd(&(bar)[XB_TMO], 1u); break; } } } } while (0)
; __device__ __forceinline__ void xcd_barrier(const XcdBarrier& b) {
;     asm volatile("s_waitcnt vmcnt(0)" ::: "memory");
;     __syncthreads();
;     if (threadIdx.x == 0) {
;         unsigned* bar = b.bar;
;         __builtin_amdgcn_s_waitcnt(0);
;         unsigned nloc = b.st[0], nx = b.st[1];
;         if (nloc == 0u) { xcd_barrier_complete(bar, b.x, nloc, nx); b.st[0] = nloc; b.st[1] = nx; }
;         const unsigned old = xb_add(&bar[XB_XSUB(b.x)], 1u);
;         const unsigned gen = old / nloc;
;         if (old + 1u == (gen + 1u) * nloc) {
;             __builtin_amdgcn_fence(__ATOMIC_RELEASE, "agent");
;             asm volatile("s_waitcnt vmcnt(0)" ::: "memory");
;             const unsigned og = xb_add(&bar[XB_TOP], 1u);
;             const unsigned tg = og / nx;
;             if (og + 1u == (tg + 1u) * nx) xb_add(&bar[XB_TOPGEN], 1u);
;             else XB_SPIN(xb_ld(&bar[XB_TOPGEN]) == tg, bar);
;             __builtin_amdgcn_fence(__ATOMIC_ACQUIRE, "agent");
;             xb_add(&bar[XB_XGEN(b.x)], 1u);
;             asm volatile("s_waitcnt vmcnt(0)" ::: "memory");
;         } else {
;             XB_SPIN(xb_ld(&bar[XB_XGEN(b.x)]) == gen, bar);
;             __builtin_amdgcn_fence(__ATOMIC_ACQUIRE, "agent");
;             asm volatile("s_waitcnt vmcnt(0)" ::: "memory");
;         }
;     }
;     __syncthreads();
; }
.LBB0_1056:
	s_cmp_lt_i32 s92, 10
	s_cselect_b64 s[8:9], -1, 0
	s_cmp_gt_i32 s93, 9
	s_cselect_b64 s[0:1], -1, 0
	s_and_b64 s[0:1], s[8:9], s[0:1]
	s_andn2_b64 vcc, exec, s[0:1]
	s_cbranch_vccnz .LBB0_1153
	s_andn2_b64 vcc, exec, s[10:11]
	s_cbranch_vccnz .LBB0_1107
	s_waitcnt vmcnt(0)
	v_cmp_eq_u32_e32 vcc, 0, v254
	s_waitcnt vmcnt(0) lgkmcnt(0)
	s_barrier
	s_and_saveexec_b64 s[0:1], vcc
	s_cbranch_execz .LBB0_1106
	s_cmp_eq_u32 s98, 1
	s_cbranch_scc0 .Lxfull_9
	s_add_i32 s99, s99, 1
	s_and_b32 s4, s2, 7
	s_lshl_b32 s4, s4, 8
	s_add_u32 s4, s90, s4
	s_addc_u32 s5, s91, 0
	s_lshr_b32 s3, s2, 3
	v_mov_b32_e32 v0, s99
	v_mov_b32_e32 v1, s3
	v_lshlrev_b32_e32 v1, 2, v1
	global_store_dword v1, v0, s[4:5] offset:512
	s_mov_b64 s[6:7], exec
	s_mov_b32 exec_lo, -1
	s_mov_b32 exec_hi, 0
	v_lshlrev_b32_e32 v2, 2, v251
	global_load_dword v3, v2, s[4:5] offset:512 sc1
	buffer_inv sc1
	s_mov_b32 s3, 0
	s_waitcnt vmcnt(1)

; __device__ __forceinline__ unsigned xb_ld(unsigned* p)              { return __hip_atomic_load(p, __ATOMIC_RELAXED, __HIP_MEMORY_SCOPE_AGENT); }
; __device__ __forceinline__ unsigned xb_add(unsigned* p, unsigned v) { return __hip_atomic_fetch_add(p, v, __ATOMIC_RELAXED, __HIP_MEMORY_SCOPE_AGENT); }
; #define XB_SPIN(cond, bar) do { unsigned _sp = 0; while (cond) { __builtin_amdgcn_s_sleep(1); \
;     if ((++_sp & 255u) == 0u) { if (xb_ld(&(bar)[XB_TMO])) break; if (_sp > XB_SPIN_CAP) { atomicAdd(&(bar)[XB_TMO], 1u); break; } } } } while (0)
; __device__ __forceinline__ void xcd_barrier(const XcdBarrier& b) {
;     asm volatile("s_waitcnt vmcnt(0)" ::: "memory");
;     __syncthreads();
;     if (threadIdx.x == 0) {
;         unsigned* bar = b.bar;
;         __builtin_amdgcn_s_waitcnt(0);
;         unsigned nloc = b.st[0], nx = b.st[1];
;         if (nloc == 0u) { xcd_barrier_complete(bar, b.x, nloc, nx); b.st[0] = nloc; b.st[1] = nx; }
;         const unsigned old = xb_add(&bar[XB_XSUB(b.x)], 1u);
;         const unsigned gen = old / nloc;
;         if (old + 1u == (gen + 1u) * nloc) {
;             __builtin_amdgcn_fence(__ATOMIC_RELEASE, "agent");
;             asm volatile("s_waitcnt vmcnt(0)" ::: "memory");
;             const unsigned og = xb_add(&bar[XB_TOP], 1u);
;             const unsigned tg = og / nx;
;             if (og + 1u == (tg + 1u) * nx) xb_add(&bar[XB_TOPGEN], 1u);
;             else XB_SPIN(xb_ld(&bar[XB_TOPGEN]) == tg, bar);
;             __builtin_amdgcn_fence(__ATOMIC_ACQUIRE, "agent");
;             xb_add(&bar[XB_XGEN(b.x)], 1u);
;             asm volatile("s_waitcnt vmcnt(0)" ::: "memory");
;         } else {
;             XB_SPIN(xb_ld(&bar[XB_XGEN(b.x)]) == gen, bar);
;             __builtin_amdgcn_fence(__ATOMIC_ACQUIRE, "agent");
;             asm volatile("s_waitcnt vmcnt(0)" ::: "memory");
;         }
;     }
;     __syncthreads();
; }
.LBB0_1153:
	s_cmp_lt_i32 s92, 11
	s_cselect_b64 s[6:7], -1, 0
	s_cmp_gt_i32 s93, 10
	s_cselect_b64 s[0:1], -1, 0
	s_and_b64 s[0:1], s[6:7], s[0:1]
	s_andn2_b64 vcc, exec, s[0:1]
	s_cbranch_vccnz .LBB0_1226
	s_andn2_b64 vcc, exec, s[8:9]
	s_cbranch_vccnz .LBB0_1204
	s_waitcnt vmcnt(0)
	v_cmp_eq_u32_e32 vcc, 0, v254
	s_waitcnt vmcnt(0) lgkmcnt(0)
	s_barrier
	s_and_saveexec_b64 s[0:1], vcc
	s_cbranch_execz .LBB0_1203
	s_cmp_eq_u32 s98, 1
	s_cbranch_scc0 .Lxfull_10
	s_add_i32 s99, s99, 1
	s_and_b32 s4, s2, 7
	s_lshl_b32 s4, s4, 8
	s_add_u32 s4, s90, s4
	s_addc_u32 s5, s91, 0
	s_lshr_b32 s3, s2, 3
	v_mov_b32_e32 v0, s99
	v_mov_b32_e32 v1, s3
	v_lshlrev_b32_e32 v1, 2, v1
	global_store_dword v1, v0, s[4:5] offset:512
	s_mov_b64 s[8:9], exec
	s_mov_b32 exec_lo, -1
	s_mov_b32 exec_hi, 0
	v_lshlrev_b32_e32 v2, 2, v251
	global_load_dword v3, v2, s[4:5] offset:512 sc1
	buffer_inv sc1
	s_mov_b32 s3, 0
	s_waitcnt vmcnt(1)

; __device__ __forceinline__ unsigned xb_ld(unsigned* p)              { return __hip_atomic_load(p, __ATOMIC_RELAXED, __HIP_MEMORY_SCOPE_AGENT); }
; __device__ __forceinline__ unsigned xb_add(unsigned* p, unsigned v) { return __hip_atomic_fetch_add(p, v, __ATOMIC_RELAXED, __HIP_MEMORY_SCOPE_AGENT); }
; #define XB_SPIN(cond, bar) do { unsigned _sp = 0; while (cond) { __builtin_amdgcn_s_sleep(1); \
;     if ((++_sp & 255u) == 0u) { if (xb_ld(&(bar)[XB_TMO])) break; if (_sp > XB_SPIN_CAP) { atomicAdd(&(bar)[XB_TMO], 1u); break; } } } } while (0)
; __device__ __forceinline__ void xcd_barrier(const XcdBarrier& b) {
;     asm volatile("s_waitcnt vmcnt(0)" ::: "memory");
;     __syncthreads();
;     if (threadIdx.x == 0) {
;         unsigned* bar = b.bar;
;         __builtin_amdgcn_s_waitcnt(0);
;         unsigned nloc = b.st[0], nx = b.st[1];
;         if (nloc == 0u) { xcd_barrier_complete(bar, b.x, nloc, nx); b.st[0] = nloc; b.st[1] = nx; }
;         const unsigned old = xb_add(&bar[XB_XSUB(b.x)], 1u);
;         const unsigned gen = old / nloc;
;         if (old + 1u == (gen + 1u) * nloc) {
;             __builtin_amdgcn_fence(__ATOMIC_RELEASE, "agent");
;             asm volatile("s_waitcnt vmcnt(0)" ::: "memory");
;             const unsigned og = xb_add(&bar[XB_TOP], 1u);
;             const unsigned tg = og / nx;
;             if (og + 1u == (tg + 1u) * nx) xb_add(&bar[XB_TOPGEN], 1u);
;             else XB_SPIN(xb_ld(&bar[XB_TOPGEN]) == tg, bar);
;             __builtin_amdgcn_fence(__ATOMIC_ACQUIRE, "agent");
;             xb_add(&bar[XB_XGEN(b.x)], 1u);
;             asm volatile("s_waitcnt vmcnt(0)" ::: "memory");
;         } else {
;             XB_SPIN(xb_ld(&bar[XB_XGEN(b.x)]) == gen, bar);
;             __builtin_amdgcn_fence(__ATOMIC_ACQUIRE, "agent");
;             asm volatile("s_waitcnt vmcnt(0)" ::: "memory");
;         }
;     }
;     __syncthreads();
; }
.LBB0_1226:
	s_cmp_lt_i32 s92, 12
	s_cselect_b64 s[8:9], -1, 0
	s_cmp_gt_i32 s93, 11
	s_cselect_b64 s[0:1], -1, 0
	s_and_b64 s[0:1], s[8:9], s[0:1]
	s_andn2_b64 vcc, exec, s[0:1]
	s_cbranch_vccnz .LBB0_1323
	s_andn2_b64 vcc, exec, s[6:7]
	s_cbranch_vccnz .LBB0_1277
	s_waitcnt vmcnt(0)
	v_cmp_eq_u32_e32 vcc, 0, v254
	s_waitcnt vmcnt(0) lgkmcnt(0)
	s_barrier
	s_and_saveexec_b64 s[0:1], vcc
	s_cbranch_execz .LBB0_1276
	s_cmp_eq_u32 s98, 1
	s_cbranch_scc0 .Lxfull_11
	s_add_i32 s99, s99, 1
	s_and_b32 s4, s2, 7
	s_lshl_b32 s4, s4, 8
	s_add_u32 s4, s90, s4
	s_addc_u32 s5, s91, 0
	s_lshr_b32 s3, s2, 3
	v_mov_b32_e32 v0, s99
	v_mov_b32_e32 v1, s3
	v_lshlrev_b32_e32 v1, 2, v1
	global_store_dword v1, v0, s[4:5] offset:512
	s_mov_b64 s[6:7], exec
	s_mov_b32 exec_lo, -1
	s_mov_b32 exec_hi, 0
	v_lshlrev_b32_e32 v2, 2, v251
	global_load_dword v3, v2, s[4:5] offset:512 sc1
	buffer_inv sc1
	s_mov_b32 s3, 0
	s_waitcnt vmcnt(1)

; __device__ __forceinline__ unsigned xb_ld(unsigned* p)              { return __hip_atomic_load(p, __ATOMIC_RELAXED, __HIP_MEMORY_SCOPE_AGENT); }
; __device__ __forceinline__ unsigned xb_add(unsigned* p, unsigned v) { return __hip_atomic_fetch_add(p, v, __ATOMIC_RELAXED, __HIP_MEMORY_SCOPE_AGENT); }
; #define XB_SPIN(cond, bar) do { unsigned _sp = 0; while (cond) { __builtin_amdgcn_s_sleep(1); \
;     if ((++_sp & 255u) == 0u) { if (xb_ld(&(bar)[XB_TMO])) break; if (_sp > XB_SPIN_CAP) { atomicAdd(&(bar)[XB_TMO], 1u); break; } } } } while (0)
; __device__ __forceinline__ void xcd_barrier(const XcdBarrier& b) {
;     asm volatile("s_waitcnt vmcnt(0)" ::: "memory");
;     __syncthreads();
;     if (threadIdx.x == 0) {
;         unsigned* bar = b.bar;
;         __builtin_amdgcn_s_waitcnt(0);
;         unsigned nloc = b.st[0], nx = b.st[1];
;         if (nloc == 0u) { xcd_barrier_complete(bar, b.x, nloc, nx); b.st[0] = nloc; b.st[1] = nx; }
;         const unsigned old = xb_add(&bar[XB_XSUB(b.x)], 1u);
;         const unsigned gen = old / nloc;
;         if (old + 1u == (gen + 1u) * nloc) {
;             __builtin_amdgcn_fence(__ATOMIC_RELEASE, "agent");
;             asm volatile("s_waitcnt vmcnt(0)" ::: "memory");
;             const unsigned og = xb_add(&bar[XB_TOP], 1u);
;             const unsigned tg = og / nx;
;             if (og + 1u == (tg + 1u) * nx) xb_add(&bar[XB_TOPGEN], 1u);
;             else XB_SPIN(xb_ld(&bar[XB_TOPGEN]) == tg, bar);
;             __builtin_amdgcn_fence(__ATOMIC_ACQUIRE, "agent");
;             xb_add(&bar[XB_XGEN(b.x)], 1u);
;             asm volatile("s_waitcnt vmcnt(0)" ::: "memory");
;         } else {
;             XB_SPIN(xb_ld(&bar[XB_XGEN(b.x)]) == gen, bar);
;             __builtin_amdgcn_fence(__ATOMIC_ACQUIRE, "agent");
;             asm volatile("s_waitcnt vmcnt(0)" ::: "memory");
;         }
;     }
;     __syncthreads();
; }
.LBB0_1323:
	s_cmp_lt_i32 s92, 13
	s_cselect_b64 s[10:11], -1, 0
	s_cmp_gt_i32 s93, 12
	s_cselect_b64 s[0:1], -1, 0
	s_and_b64 s[0:1], s[10:11], s[0:1]
	s_andn2_b64 vcc, exec, s[0:1]
	s_cbranch_vccnz .LBB0_1504
	s_andn2_b64 vcc, exec, s[8:9]
	s_cbranch_vccnz .LBB0_1374
	s_waitcnt vmcnt(0)
	v_cmp_eq_u32_e32 vcc, 0, v254
	s_waitcnt vmcnt(0) lgkmcnt(0)
	s_barrier
	s_and_saveexec_b64 s[0:1], vcc
	s_cbranch_execz .LBB0_1373
	s_cmp_eq_u32 s98, 1
	s_cbranch_scc0 .Lxfull_12
	s_add_i32 s99, s99, 1
	s_and_b32 s4, s2, 7
	s_lshl_b32 s4, s4, 8
	s_add_u32 s4, s90, s4
	s_addc_u32 s5, s91, 0
	s_lshr_b32 s3, s2, 3
	v_mov_b32_e32 v0, s99
	v_mov_b32_e32 v1, s3
	v_lshlrev_b32_e32 v1, 2, v1
	global_store_dword v1, v0, s[4:5] offset:512
	s_mov_b64 s[6:7], exec
	s_mov_b32 exec_lo, -1
	s_mov_b32 exec_hi, 0
	v_lshlrev_b32_e32 v2, 2, v251
	global_load_dword v3, v2, s[4:5] offset:512 sc1
	buffer_inv sc1
	s_mov_b32 s3, 0
	s_waitcnt vmcnt(1)

; __device__ __forceinline__ unsigned xb_ld(unsigned* p)              { return __hip_atomic_load(p, __ATOMIC_RELAXED, __HIP_MEMORY_SCOPE_AGENT); }
; __device__ __forceinline__ unsigned xb_add(unsigned* p, unsigned v) { return __hip_atomic_fetch_add(p, v, __ATOMIC_RELAXED, __HIP_MEMORY_SCOPE_AGENT); }
; #define XB_SPIN(cond, bar) do { unsigned _sp = 0; while (cond) { __builtin_amdgcn_s_sleep(1); \
;     if ((++_sp & 255u) == 0u) { if (xb_ld(&(bar)[XB_TMO])) break; if (_sp > XB_SPIN_CAP) { atomicAdd(&(bar)[XB_TMO], 1u); break; } } } } while (0)
; __device__ __forceinline__ void xcd_barrier(const XcdBarrier& b) {
;     asm volatile("s_waitcnt vmcnt(0)" ::: "memory");
;     __syncthreads();
;     if (threadIdx.x == 0) {
;         unsigned* bar = b.bar;
;         __builtin_amdgcn_s_waitcnt(0);
;         unsigned nloc = b.st[0], nx = b.st[1];
;         if (nloc == 0u) { xcd_barrier_complete(bar, b.x, nloc, nx); b.st[0] = nloc; b.st[1] = nx; }
;         const unsigned old = xb_add(&bar[XB_XSUB(b.x)], 1u);
;         const unsigned gen = old / nloc;
;         if (old + 1u == (gen + 1u) * nloc) {
;             __builtin_amdgcn_fence(__ATOMIC_RELEASE, "agent");
;             asm volatile("s_waitcnt vmcnt(0)" ::: "memory");
;             const unsigned og = xb_add(&bar[XB_TOP], 1u);
;             const unsigned tg = og / nx;
;             if (og + 1u == (tg + 1u) * nx) xb_add(&bar[XB_TOPGEN], 1u);
;             else XB_SPIN(xb_ld(&bar[XB_TOPGEN]) == tg, bar);
;             __builtin_amdgcn_fence(__ATOMIC_ACQUIRE, "agent");
;             xb_add(&bar[XB_XGEN(b.x)], 1u);
;             asm volatile("s_waitcnt vmcnt(0)" ::: "memory");
;         } else {
;             XB_SPIN(xb_ld(&bar[XB_XGEN(b.x)]) == gen, bar);
;             __builtin_amdgcn_fence(__ATOMIC_ACQUIRE, "agent");
;             asm volatile("s_waitcnt vmcnt(0)" ::: "memory");
;         }
;     }
;     __syncthreads();
; }
.LBB0_1587:
	s_cmp_lt_i32 s92, 15
	s_cselect_b64 s[0:1], -1, 0
	s_cmp_gt_i32 s93, 14
	s_cselect_b64 s[4:5], -1, 0
	s_and_b64 s[4:5], s[0:1], s[4:5]
	v_readlane_b32 s64, v255, 4
	s_andn2_b64 vcc, exec, s[4:5]
	v_readlane_b32 s68, v255, 8
	v_readlane_b32 s69, v255, 9
	v_readlane_b32 s78, v255, 18
	v_readlane_b32 s79, v255, 19
	v_readlane_b32 s65, v255, 5
	v_readlane_b32 s66, v255, 6
	v_readlane_b32 s67, v255, 7
	v_readlane_b32 s70, v255, 10
	v_readlane_b32 s71, v255, 11
	v_readlane_b32 s72, v255, 12
	v_readlane_b32 s73, v255, 13
	v_readlane_b32 s74, v255, 14
	v_readlane_b32 s75, v255, 15
	v_readlane_b32 s76, v255, 16
	v_readlane_b32 s77, v255, 17
	s_cbranch_vccnz .LBB0_1648
	s_andn2_b64 vcc, exec, s[46:47]
	s_cbranch_vccnz .LBB0_1638
	s_waitcnt vmcnt(0)
	v_cmp_eq_u32_e32 vcc, 0, v254
	s_waitcnt vmcnt(0) lgkmcnt(0)
	s_barrier
	s_and_saveexec_b64 s[4:5], vcc
	s_cbranch_execz .LBB0_1637
	s_cmp_eq_u32 s98, 1
	s_cbranch_scc0 .Lxfull_14
	s_add_i32 s99, s99, 1
	s_and_b32 s6, s2, 7
	s_lshl_b32 s6, s6, 8
	s_add_u32 s6, s90, s6
	s_addc_u32 s7, s91, 0
	s_lshr_b32 s3, s2, 3
	v_mov_b32_e32 v0, s99
	v_mov_b32_e32 v1, s3
	v_lshlrev_b32_e32 v1, 2, v1
	global_store_dword v1, v0, s[6:7] offset:512
	s_mov_b64 s[8:9], exec
	s_mov_b32 exec_lo, -1
	s_mov_b32 exec_hi, 0
	v_lshlrev_b32_e32 v2, 2, v251
	global_load_dword v3, v2, s[6:7] offset:512 sc1
	buffer_inv sc1
	s_mov_b32 s3, 0
	s_waitcnt vmcnt(1)

; __device__ __forceinline__ unsigned xb_ld(unsigned* p)              { return __hip_atomic_load(p, __ATOMIC_RELAXED, __HIP_MEMORY_SCOPE_AGENT); }
; __device__ __forceinline__ unsigned xb_add(unsigned* p, unsigned v) { return __hip_atomic_fetch_add(p, v, __ATOMIC_RELAXED, __HIP_MEMORY_SCOPE_AGENT); }
; #define XB_SPIN(cond, bar) do { unsigned _sp = 0; while (cond) { __builtin_amdgcn_s_sleep(1); \
;     if ((++_sp & 255u) == 0u) { if (xb_ld(&(bar)[XB_TMO])) break; if (_sp > XB_SPIN_CAP) { atomicAdd(&(bar)[XB_TMO], 1u); break; } } } } while (0)
; __device__ __forceinline__ void xcd_barrier(const XcdBarrier& b) {
;     asm volatile("s_waitcnt vmcnt(0)" ::: "memory");
;     __syncthreads();
;     if (threadIdx.x == 0) {
;         unsigned* bar = b.bar;
;         __builtin_amdgcn_s_waitcnt(0);
;         unsigned nloc = b.st[0], nx = b.st[1];
;         if (nloc == 0u) { xcd_barrier_complete(bar, b.x, nloc, nx); b.st[0] = nloc; b.st[1] = nx; }
;         const unsigned old = xb_add(&bar[XB_XSUB(b.x)], 1u);
;         const unsigned gen = old / nloc;
;         if (old + 1u == (gen + 1u) * nloc) {
;             __builtin_amdgcn_fence(__ATOMIC_RELEASE, "agent");
;             asm volatile("s_waitcnt vmcnt(0)" ::: "memory");
;             const unsigned og = xb_add(&bar[XB_TOP], 1u);
;             const unsigned tg = og / nx;
;             if (og + 1u == (tg + 1u) * nx) xb_add(&bar[XB_TOPGEN], 1u);
;             else XB_SPIN(xb_ld(&bar[XB_TOPGEN]) == tg, bar);
;             __builtin_amdgcn_fence(__ATOMIC_ACQUIRE, "agent");
;             xb_add(&bar[XB_XGEN(b.x)], 1u);
;             asm volatile("s_waitcnt vmcnt(0)" ::: "memory");
;         } else {
;             XB_SPIN(xb_ld(&bar[XB_XGEN(b.x)]) == gen, bar);
;             __builtin_amdgcn_fence(__ATOMIC_ACQUIRE, "agent");
;             asm volatile("s_waitcnt vmcnt(0)" ::: "memory");
;         }
;     }
;     __syncthreads();
; }
.LBB0_1648:
	s_cmp_lt_i32 s92, 16
	s_cselect_b64 s[40:41], -1, 0
	s_cmp_gt_i32 s93, 15
	s_cselect_b64 s[4:5], -1, 0
	s_and_b64 s[4:5], s[40:41], s[4:5]
	s_andn2_b64 vcc, exec, s[4:5]
	s_cbranch_vccnz .LBB0_1773
	s_andn2_b64 vcc, exec, s[0:1]
	s_cbranch_vccnz .LBB0_1699
	s_waitcnt vmcnt(0)
	v_cmp_eq_u32_e32 vcc, 0, v254
	s_waitcnt vmcnt(0) lgkmcnt(0)
	s_barrier
	s_and_saveexec_b64 s[0:1], vcc
	s_cbranch_execz .LBB0_1698
	s_cmp_eq_u32 s98, 1
	s_cbranch_scc0 .Lxfull_15
	s_add_i32 s99, s99, 1
	s_and_b32 s4, s2, 7
	s_lshl_b32 s4, s4, 8
	s_add_u32 s4, s90, s4
	s_addc_u32 s5, s91, 0
	s_lshr_b32 s3, s2, 3
	v_mov_b32_e32 v0, s99
	v_mov_b32_e32 v1, s3
	v_lshlrev_b32_e32 v1, 2, v1
	global_store_dword v1, v0, s[4:5] offset:512
	s_mov_b64 s[6:7], exec
	s_mov_b32 exec_lo, -1
	s_mov_b32 exec_hi, 0
	v_lshlrev_b32_e32 v2, 2, v251
	global_load_dword v3, v2, s[4:5] offset:512 sc1
	buffer_inv sc1
	s_mov_b32 s3, 0
	s_waitcnt vmcnt(1)

; __device__ __forceinline__ unsigned xb_ld(unsigned* p)              { return __hip_atomic_load(p, __ATOMIC_RELAXED, __HIP_MEMORY_SCOPE_AGENT); }
; __device__ __forceinline__ unsigned xb_add(unsigned* p, unsigned v) { return __hip_atomic_fetch_add(p, v, __ATOMIC_RELAXED, __HIP_MEMORY_SCOPE_AGENT); }
; #define XB_SPIN(cond, bar) do { unsigned _sp = 0; while (cond) { __builtin_amdgcn_s_sleep(1); \
;     if ((++_sp & 255u) == 0u) { if (xb_ld(&(bar)[XB_TMO])) break; if (_sp > XB_SPIN_CAP) { atomicAdd(&(bar)[XB_TMO], 1u); break; } } } } while (0)
; __device__ __forceinline__ void xcd_barrier(const XcdBarrier& b) {
;     asm volatile("s_waitcnt vmcnt(0)" ::: "memory");
;     __syncthreads();
;     if (threadIdx.x == 0) {
;         unsigned* bar = b.bar;
;         __builtin_amdgcn_s_waitcnt(0);
;         unsigned nloc = b.st[0], nx = b.st[1];
;         if (nloc == 0u) { xcd_barrier_complete(bar, b.x, nloc, nx); b.st[0] = nloc; b.st[1] = nx; }
;         const unsigned old = xb_add(&bar[XB_XSUB(b.x)], 1u);
;         const unsigned gen = old / nloc;
;         if (old + 1u == (gen + 1u) * nloc) {
;             __builtin_amdgcn_fence(__ATOMIC_RELEASE, "agent");
;             asm volatile("s_waitcnt vmcnt(0)" ::: "memory");
;             const unsigned og = xb_add(&bar[XB_TOP], 1u);
;             const unsigned tg = og / nx;
;             if (og + 1u == (tg + 1u) * nx) xb_add(&bar[XB_TOPGEN], 1u);
;             else XB_SPIN(xb_ld(&bar[XB_TOPGEN]) == tg, bar);
;             __builtin_amdgcn_fence(__ATOMIC_ACQUIRE, "agent");
;             xb_add(&bar[XB_XGEN(b.x)], 1u);
;             asm volatile("s_waitcnt vmcnt(0)" ::: "memory");
;         } else {
;             XB_SPIN(xb_ld(&bar[XB_XGEN(b.x)]) == gen, bar);
;             __builtin_amdgcn_fence(__ATOMIC_ACQUIRE, "agent");
;             asm volatile("s_waitcnt vmcnt(0)" ::: "memory");
;         }
;     }
;     __syncthreads();
; }
.LBB0_1866:
	s_cmp_lt_i32 s92, 18
	s_cselect_b64 s[10:11], -1, 0
	s_cmp_gt_i32 s93, 17
	s_cselect_b64 s[0:1], -1, 0
	s_and_b64 s[0:1], s[10:11], s[0:1]
	s_andn2_b64 vcc, exec, s[0:1]
	s_cbranch_vccnz .LBB0_1939
	s_andn2_b64 vcc, exec, s[6:7]
	s_cbranch_vccnz .LBB0_1917
	s_waitcnt vmcnt(0)
	v_cmp_eq_u32_e32 vcc, 0, v254
	s_waitcnt vmcnt(0) lgkmcnt(0)
	s_barrier
	s_and_saveexec_b64 s[0:1], vcc
	s_cbranch_execz .LBB0_1916
	s_cmp_eq_u32 s98, 1
	s_cbranch_scc0 .Lxfull_17
	s_add_i32 s99, s99, 1
	s_and_b32 s4, s2, 7
	s_lshl_b32 s4, s4, 8
	s_add_u32 s4, s90, s4
	s_addc_u32 s5, s91, 0
	s_lshr_b32 s3, s2, 3
	v_mov_b32_e32 v0, s99
	v_mov_b32_e32 v1, s3
	v_lshlrev_b32_e32 v1, 2, v1
	global_store_dword v1, v0, s[4:5] offset:512
	s_mov_b64 s[6:7], exec
	s_mov_b32 exec_lo, -1
	s_mov_b32 exec_hi, 0
	v_lshlrev_b32_e32 v2, 2, v251
	global_load_dword v3, v2, s[4:5] offset:512 sc1
	buffer_inv sc1
	s_mov_b32 s3, 0
	s_waitcnt vmcnt(1)

; __device__ __forceinline__ unsigned xb_ld(unsigned* p)              { return __hip_atomic_load(p, __ATOMIC_RELAXED, __HIP_MEMORY_SCOPE_AGENT); }
; __device__ __forceinline__ unsigned xb_add(unsigned* p, unsigned v) { return __hip_atomic_fetch_add(p, v, __ATOMIC_RELAXED, __HIP_MEMORY_SCOPE_AGENT); }
; #define XB_SPIN(cond, bar) do { unsigned _sp = 0; while (cond) { __builtin_amdgcn_s_sleep(1); \
;     if ((++_sp & 255u) == 0u) { if (xb_ld(&(bar)[XB_TMO])) break; if (_sp > XB_SPIN_CAP) { atomicAdd(&(bar)[XB_TMO], 1u); break; } } } } while (0)
; __device__ __forceinline__ void xcd_barrier(const XcdBarrier& b) {
;     asm volatile("s_waitcnt vmcnt(0)" ::: "memory");
;     __syncthreads();
;     if (threadIdx.x == 0) {
;         unsigned* bar = b.bar;
;         __builtin_amdgcn_s_waitcnt(0);
;         unsigned nloc = b.st[0], nx = b.st[1];
;         if (nloc == 0u) { xcd_barrier_complete(bar, b.x, nloc, nx); b.st[0] = nloc; b.st[1] = nx; }
;         const unsigned old = xb_add(&bar[XB_XSUB(b.x)], 1u);
;         const unsigned gen = old / nloc;
;         if (old + 1u == (gen + 1u) * nloc) {
;             __builtin_amdgcn_fence(__ATOMIC_RELEASE, "agent");
;             asm volatile("s_waitcnt vmcnt(0)" ::: "memory");
;             const unsigned og = xb_add(&bar[XB_TOP], 1u);
;             const unsigned tg = og / nx;
;             if (og + 1u == (tg + 1u) * nx) xb_add(&bar[XB_TOPGEN], 1u);
;             else XB_SPIN(xb_ld(&bar[XB_TOPGEN]) == tg, bar);
;             __builtin_amdgcn_fence(__ATOMIC_ACQUIRE, "agent");
;             xb_add(&bar[XB_XGEN(b.x)], 1u);
;             asm volatile("s_waitcnt vmcnt(0)" ::: "memory");
;         } else {
;             XB_SPIN(xb_ld(&bar[XB_XGEN(b.x)]) == gen, bar);
;             __builtin_amdgcn_fence(__ATOMIC_ACQUIRE, "agent");
;             asm volatile("s_waitcnt vmcnt(0)" ::: "memory");
;         }
;     }
;     __syncthreads();
; }
.LBB0_1939:
	s_cmp_lt_i32 s92, 19
	s_cselect_b64 s[8:9], -1, 0
	s_cmp_gt_i32 s93, 18
	s_cselect_b64 s[0:1], -1, 0
	s_and_b64 s[0:1], s[8:9], s[0:1]
	s_andn2_b64 vcc, exec, s[0:1]
	s_cbranch_vccnz .LBB0_2036
	s_andn2_b64 vcc, exec, s[10:11]
	s_cbranch_vccnz .LBB0_1990
	s_waitcnt vmcnt(0)
	v_cmp_eq_u32_e32 vcc, 0, v254
	s_waitcnt vmcnt(0) lgkmcnt(0)
	s_barrier
	s_and_saveexec_b64 s[0:1], vcc
	s_cbranch_execz .LBB0_1989
	s_cmp_eq_u32 s98, 1
	s_cbranch_scc0 .Lxfull_18
	s_add_i32 s99, s99, 1
	s_and_b32 s4, s2, 7
	s_lshl_b32 s4, s4, 8
	s_add_u32 s4, s90, s4
	s_addc_u32 s5, s91, 0
	s_lshr_b32 s3, s2, 3
	v_mov_b32_e32 v0, s99
	v_mov_b32_e32 v1, s3
	v_lshlrev_b32_e32 v1, 2, v1
	global_store_dword v1, v0, s[4:5] offset:512
	s_mov_b64 s[6:7], exec
	s_mov_b32 exec_lo, -1
	s_mov_b32 exec_hi, 0
	v_lshlrev_b32_e32 v2, 2, v251
	global_load_dword v3, v2, s[4:5] offset:512 sc1
	buffer_inv sc1
	s_mov_b32 s3, 0
	s_waitcnt vmcnt(1)

; __device__ __forceinline__ unsigned xb_ld(unsigned* p)              { return __hip_atomic_load(p, __ATOMIC_RELAXED, __HIP_MEMORY_SCOPE_AGENT); }
; __device__ __forceinline__ unsigned xb_add(unsigned* p, unsigned v) { return __hip_atomic_fetch_add(p, v, __ATOMIC_RELAXED, __HIP_MEMORY_SCOPE_AGENT); }
; #define XB_SPIN(cond, bar) do { unsigned _sp = 0; while (cond) { __builtin_amdgcn_s_sleep(1); \
;     if ((++_sp & 255u) == 0u) { if (xb_ld(&(bar)[XB_TMO])) break; if (_sp > XB_SPIN_CAP) { atomicAdd(&(bar)[XB_TMO], 1u); break; } } } } while (0)
; __device__ __forceinline__ void xcd_barrier(const XcdBarrier& b) {
;     asm volatile("s_waitcnt vmcnt(0)" ::: "memory");
;     __syncthreads();
;     if (threadIdx.x == 0) {
;         unsigned* bar = b.bar;
;         __builtin_amdgcn_s_waitcnt(0);
;         unsigned nloc = b.st[0], nx = b.st[1];
;         if (nloc == 0u) { xcd_barrier_complete(bar, b.x, nloc, nx); b.st[0] = nloc; b.st[1] = nx; }
;         const unsigned old = xb_add(&bar[XB_XSUB(b.x)], 1u);
;         const unsigned gen = old / nloc;
;         if (old + 1u == (gen + 1u) * nloc) {
;             __builtin_amdgcn_fence(__ATOMIC_RELEASE, "agent");
;             asm volatile("s_waitcnt vmcnt(0)" ::: "memory");
;             const unsigned og = xb_add(&bar[XB_TOP], 1u);
;             const unsigned tg = og / nx;
;             if (og + 1u == (tg + 1u) * nx) xb_add(&bar[XB_TOPGEN], 1u);
;             else XB_SPIN(xb_ld(&bar[XB_TOPGEN]) == tg, bar);
;             __builtin_amdgcn_fence(__ATOMIC_ACQUIRE, "agent");
;             xb_add(&bar[XB_XGEN(b.x)], 1u);
;             asm volatile("s_waitcnt vmcnt(0)" ::: "memory");
;         } else {
;             XB_SPIN(xb_ld(&bar[XB_XGEN(b.x)]) == gen, bar);
;             __builtin_amdgcn_fence(__ATOMIC_ACQUIRE, "agent");
;             asm volatile("s_waitcnt vmcnt(0)" ::: "memory");
;         }
;     }
;     __syncthreads();
; }
.LBB0_2036:
	s_cmp_lt_i32 s92, 20
	s_cselect_b64 s[0:1], -1, 0
	s_cmp_gt_i32 s93, 19
	s_cselect_b64 s[4:5], -1, 0
	s_and_b64 s[0:1], s[0:1], s[4:5]
	s_andn2_b64 vcc, exec, s[0:1]
	s_cbranch_vccnz .LBB0_2090
	s_andn2_b64 vcc, exec, s[8:9]
	s_cbranch_vccnz .LBB0_2087
	s_waitcnt vmcnt(0)
	v_cmp_eq_u32_e32 vcc, 0, v254
	s_waitcnt vmcnt(0) lgkmcnt(0)
	s_barrier
	s_and_saveexec_b64 s[0:1], vcc
	s_cbranch_execz .LBB0_2086
	s_cmp_eq_u32 s98, 1
	s_cbranch_scc0 .Lxfull_19
	s_add_i32 s99, s99, 1
	s_and_b32 s4, s2, 7
	s_lshl_b32 s4, s4, 8
	s_add_u32 s4, s90, s4
	s_addc_u32 s5, s91, 0
	s_lshr_b32 s3, s2, 3
	v_mov_b32_e32 v0, s99
	v_mov_b32_e32 v1, s3
	v_lshlrev_b32_e32 v1, 2, v1
	global_store_dword v1, v0, s[4:5] offset:512
	s_mov_b64 s[6:7], exec
	s_mov_b32 exec_lo, -1
	s_mov_b32 exec_hi, 0
	v_lshlrev_b32_e32 v2, 2, v251
	global_load_dword v3, v2, s[4:5] offset:512 sc1
	buffer_inv sc1
	s_mov_b32 s3, 0
	s_waitcnt vmcnt(1)
